# P7 epilogue: conv halo for row blocks inside a wave taken from registers with DPP row_ror (bound_ctrl:0 merge) instead of LDS exchange; unneeded halo LDS writes removed
# speedup vs baseline: 1.0322x; 1.0023x over previous
; #define LAS __attribute__((address_space(3)))
; #define FOR_AI_M _Pragma("unroll") for (int ai = 0; ai < 2; ++ai) _Pragma("unroll") for (int m = 0; m < 4; ++m)
; #define FOR_BJ_N _Pragma("unroll") for (int bj = 0; bj < 2; ++bj) _Pragma("unroll") for (int n = 0; n < 2; ++n)
;     __device__ __forceinline__ void operator()(EPI_ARGS) const {
;     ...
;         FOR_AI_M { rsv[ai][m] = pf[ai * 64 + m * 16 + fr]; }
;         f32x4 W0[2], W1[2], W2[2], BB[2];
; #pragma unroll
;         for (int n = 0; n < 2; ++n) { const int c8 = 8 * fq + 4 * n;
;             W0[n] = *(const LAS f32x4*)(pf + 128 + c8); W1[n] = *(const LAS f32x4*)(pf + 128 + 32 + c8); W2[n] = *(const LAS f32x4*)(pf + 128 + 64 + c8); BB[n] = *(const LAS f32x4*)(pf + 128 + 96 + c8); }
;         FOR_AI_M {
;             const float rs = rsqrtf(rsv[ai][m] * (1.0f / 2048.0f) + EPS);
;             FOR_BJ_N acc[ai][bj][m][n] *= rs;
;             if (fr >= 14) {
;                 const int rb = ai * 8 + wr * 4 + m;
; #pragma unroll
;                 for (int n = 0; n < 2; ++n) *(LAS f32x4*)(halo + ((rb * 2 + (fr - 14)) * 128 + wc * 32 + 8 * fq + 4 * n)) = acc[ai][0][m][n];
;             }
;         }
.LBB0_1089:
	v_mov_b32_e32 v191, v215
	v_mov_b32_e32 v168, v216
	s_mov_b32 s81, s33
	s_mov_b32 s4, s19
	s_lshl_b32 s82, s81, 2
	s_add_i32 s6, s82, s4
	s_mulk_i32 s6, 0x600
	s_add_i32 s6, s6, 0
	s_add_i32 s6, s6, 0x24040
	v_lshl_add_u32 v128, v191, 2, s6
	v_lshlrev_b32_e32 v169, 5, v168
	ds_read2_b32 v[166:167], v128 offset1:16
	ds_read2_b32 v[164:165], v128 offset0:32 offset1:48
	ds_read2_b32 v[162:163], v128 offset0:64 offset1:80
	ds_read2_b32 v[160:161], v128 offset0:96 offset1:112
	v_add_u32_e32 v140, s6, v169
	ds_read_b128 v[144:147], v140 offset:512
	ds_read_b128 v[128:131], v140 offset:528
	ds_read_b128 v[148:151], v140 offset:640
	ds_read_b128 v[132:135], v140 offset:656
	ds_read_b128 v[152:155], v140 offset:768
	ds_read_b128 v[136:139], v140 offset:784
	ds_read_b128 v[156:159], v140 offset:896
	ds_read_b128 v[140:143], v140 offset:912
	s_waitcnt lgkmcnt(0)
	v_fmamk_f32 v166, v166, 0x3a000000, v221
	v_mul_f32_e32 v187, 0x4b800000, v166
	v_cmp_gt_f32_e64 s[46:47], s72, v166
	v_lshlrev_b32_e32 v195, 9, v191
	v_cmp_gt_i32_e64 s[44:45], 14, v191
	v_cndmask_b32_e64 v166, v166, v187, s[46:47]
	v_rsq_f32_e32 v187, v166
	v_cmp_lt_i32_e32 vcc, 13, v191
	v_add_u32_e32 v166, s71, v195
	s_lshl_b32 s8, s4, 7
	v_mul_f32_e32 v189, 0x45800000, v187
	v_cndmask_b32_e64 v208, v187, v189, s[46:47]
	v_pk_mul_f32 v[66:67], v[66:67], v[208:209] op_sel_hi:[1,0]
	v_pk_mul_f32 v[64:65], v[64:65], v[208:209] op_sel_hi:[1,0]
	v_pk_mul_f32 v[126:127], v[126:127], v[208:209] op_sel_hi:[1,0]
	v_pk_mul_f32 v[124:125], v[124:125], v[208:209] op_sel_hi:[1,0]
	s_and_saveexec_b64 s[6:7], vcc
	s_cbranch_execz .LBB0_1091
	s_lshl_b32 s9, s81, 12
	s_add_i32 s9, s8, s9
	v_add_u32_e32 v187, s9, v166
	v_add3_u32 v187, v187, v169, s73
.LBB0_1091:
	s_or_b64 exec, exec, s[6:7]
	v_fmamk_f32 v167, v167, 0x3a000000, v221
	v_mul_f32_e32 v187, 0x4b800000, v167
	v_cmp_gt_f32_e64 s[46:47], s72, v167
	s_nop 1
	v_cndmask_b32_e64 v167, v167, v187, s[46:47]
	v_rsq_f32_e32 v167, v167
	s_nop 0
	v_mul_f32_e32 v187, 0x45800000, v167
	v_cndmask_b32_e64 v206, v167, v187, s[46:47]
	v_pk_mul_f32 v[122:123], v[122:123], v[206:207] op_sel_hi:[1,0]
	v_pk_mul_f32 v[120:121], v[120:121], v[206:207] op_sel_hi:[1,0]
	v_pk_mul_f32 v[118:119], v[118:119], v[206:207] op_sel_hi:[1,0]
	v_pk_mul_f32 v[116:117], v[116:117], v[206:207] op_sel_hi:[1,0]
	s_and_saveexec_b64 s[6:7], vcc
	s_cbranch_execz .LBB0_1093
	s_lshl_b32 s9, s81, 12
	s_add_i32 s9, s8, s9
	v_add_u32_e32 v167, s9, v166
	s_movk_i32 s9, 0xe800
	v_add3_u32 v167, v167, v169, s9
.LBB0_1093:
	s_or_b64 exec, exec, s[6:7]
	v_fmamk_f32 v164, v164, 0x3a000000, v221
	v_mul_f32_e32 v167, 0x4b800000, v164
	v_cmp_gt_f32_e64 s[46:47], s72, v164
	s_nop 1
	v_cndmask_b32_e64 v164, v164, v167, s[46:47]
	v_rsq_f32_e32 v164, v164
	s_nop 0
	v_mul_f32_e32 v167, 0x45800000, v164
	v_cndmask_b32_e64 v204, v164, v167, s[46:47]
	v_pk_mul_f32 v[114:115], v[114:115], v[204:205] op_sel_hi:[1,0]
	v_pk_mul_f32 v[112:113], v[112:113], v[204:205] op_sel_hi:[1,0]
	v_pk_mul_f32 v[110:111], v[110:111], v[204:205] op_sel_hi:[1,0]
	v_pk_mul_f32 v[108:109], v[108:109], v[204:205] op_sel_hi:[1,0]
	s_and_saveexec_b64 s[6:7], vcc
	s_cbranch_execz .LBB0_1095
	s_lshl_b32 s9, s81, 12
	s_add_i32 s9, s8, s9
	v_add_u32_e32 v164, s9, v166
	s_movk_i32 s9, 0xec00
	v_add3_u32 v164, v164, v169, s9
.LBB0_1095:
	s_or_b64 exec, exec, s[6:7]
	v_fmamk_f32 v164, v165, 0x3a000000, v221
	v_mul_f32_e32 v165, 0x4b800000, v164
	v_cmp_gt_f32_e64 s[46:47], s72, v164
	s_nop 1
	v_cndmask_b32_e64 v164, v164, v165, s[46:47]
	v_rsq_f32_e32 v164, v164
	s_nop 0
	v_mul_f32_e32 v165, 0x45800000, v164
	v_cndmask_b32_e64 v202, v164, v165, s[46:47]
	v_pk_mul_f32 v[106:107], v[106:107], v[202:203] op_sel_hi:[1,0]
	v_pk_mul_f32 v[104:105], v[104:105], v[202:203] op_sel_hi:[1,0]
	v_pk_mul_f32 v[102:103], v[102:103], v[202:203] op_sel_hi:[1,0]
	v_pk_mul_f32 v[100:101], v[100:101], v[202:203] op_sel_hi:[1,0]
	s_and_saveexec_b64 s[6:7], vcc
	s_cbranch_execz .LBB0_1097
	s_lshl_b32 s9, s81, 12
	s_add_i32 s9, s8, s9
	v_add_u32_e32 v164, s9, v166
	s_movk_i32 s9, 0xf000
	v_add3_u32 v164, v164, v169, s9
	ds_write_b128 v164, v[104:107]
	ds_write_b128 v164, v[100:103] offset:16

; #define LAS __attribute__((address_space(3)))
; #define FOR_AI_M _Pragma("unroll") for (int ai = 0; ai < 2; ++ai) _Pragma("unroll") for (int m = 0; m < 4; ++m)
; #define FOR_BJ_N _Pragma("unroll") for (int bj = 0; bj < 2; ++bj) _Pragma("unroll") for (int n = 0; n < 2; ++n)
;     __device__ __forceinline__ void operator()(EPI_ARGS) const {
;     ...
;         FOR_AI_M {
;             const float rs = rsqrtf(rsv[ai][m] * (1.0f / 2048.0f) + EPS);
;             FOR_BJ_N acc[ai][bj][m][n] *= rs;
;             if (fr >= 14) {
;                 const int rb = ai * 8 + wr * 4 + m;
; #pragma unroll
;                 for (int n = 0; n < 2; ++n) *(LAS f32x4*)(halo + ((rb * 2 + (fr - 14)) * 128 + wc * 32 + 8 * fq + 4 * n)) = acc[ai][0][m][n];
;             }
;         }
.LBB0_1099:
	s_or_b64 exec, exec, s[6:7]
	v_fmamk_f32 v162, v163, 0x3a000000, v221
	v_cmp_gt_f32_e64 s[46:47], s72, v162
	s_and_saveexec_b64 s[6:7], s[44:45]
	s_xor_b64 s[6:7], exec, s[6:7]
	s_lshl_b32 s9, s81, 12
	s_or_saveexec_b64 s[6:7], s[6:7]
	v_mul_f32_e32 v163, 0x4b800000, v162
	v_cndmask_b32_e64 v162, v162, v163, s[46:47]
	v_rsq_f32_e32 v162, v162
	s_nop 0
	v_mul_f32_e32 v163, 0x45800000, v162
	v_cndmask_b32_e64 v198, v162, v163, s[46:47]
	v_pk_mul_f32 v[54:55], v[54:55], v[198:199] op_sel_hi:[1,0]
	v_pk_mul_f32 v[52:53], v[52:53], v[198:199] op_sel_hi:[1,0]
	v_pk_mul_f32 v[50:51], v[50:51], v[198:199] op_sel_hi:[1,0]
	v_pk_mul_f32 v[48:49], v[48:49], v[198:199] op_sel_hi:[1,0]
	v_mov_b32_e32 v162, s9
	s_xor_b64 exec, exec, s[6:7]
	s_cbranch_execz .LBB0_1103
	s_lshl_b32 s9, s81, 12
	s_add_i32 s10, s8, s9
	v_add3_u32 v162, s10, v166, v169
	v_mov_b32_e32 v162, s9
.LBB0_1103:
	s_or_b64 exec, exec, s[6:7]
	v_fmamk_f32 v160, v160, 0x3a000000, v221
	v_mul_f32_e32 v163, 0x4b800000, v160
	v_cmp_gt_f32_e64 s[44:45], s72, v160
	s_nop 1
	v_cndmask_b32_e64 v160, v160, v163, s[44:45]
	v_rsq_f32_e32 v160, v160
	s_nop 0
	v_mul_f32_e32 v163, 0x45800000, v160
	v_cndmask_b32_e64 v196, v160, v163, s[44:45]
	v_add_u32_e32 v160, v166, v162
	v_pk_mul_f32 v[46:47], v[46:47], v[196:197] op_sel_hi:[1,0]
	v_pk_mul_f32 v[44:45], v[44:45], v[196:197] op_sel_hi:[1,0]
	v_pk_mul_f32 v[42:43], v[42:43], v[196:197] op_sel_hi:[1,0]
	v_pk_mul_f32 v[40:41], v[40:41], v[196:197] op_sel_hi:[1,0]
	v_add3_u32 v160, v160, s8, v169
	s_and_saveexec_b64 s[6:7], vcc
	s_cbranch_execz .LBB0_1105
.LBB0_1105:
	s_or_b64 exec, exec, s[6:7]
	v_fmamk_f32 v161, v161, 0x3a000000, v221
	v_mul_f32_e32 v163, 0x4b800000, v161
	v_cmp_gt_f32_e64 s[44:45], s72, v161
	s_nop 1
	v_cndmask_b32_e64 v161, v161, v163, s[44:45]
	v_rsq_f32_e32 v161, v161
	s_nop 0
	v_mul_f32_e32 v163, 0x45800000, v161
	v_cndmask_b32_e64 v194, v161, v163, s[44:45]
	v_pk_mul_f32 v[38:39], v[38:39], v[194:195] op_sel_hi:[1,0]
	v_pk_mul_f32 v[36:37], v[36:37], v[194:195] op_sel_hi:[1,0]
	v_pk_mul_f32 v[34:35], v[34:35], v[194:195] op_sel_hi:[1,0]
	v_pk_mul_f32 v[32:33], v[32:33], v[194:195] op_sel_hi:[1,0]
	s_and_saveexec_b64 s[6:7], vcc
	s_cbranch_execz .LBB0_1107
	ds_write_b128 v160, v[36:39] offset:4096
	ds_write_b128 v160, v[32:35] offset:4112

; #define LAS __attribute__((address_space(3)))
; __device__ __forceinline__ u32x2 pack4(f32x4 v) { u32x2 r; r.x = cvt_pk(v[0], v[1]); r.y = cvt_pk(v[2], v[3]); return r; }
; __device__ __forceinline__ float dpp_shr1(float v) { return __builtin_bit_cast(float, __builtin_amdgcn_update_dpp(0, __builtin_bit_cast(int, v), 0x111, 0xf, 0xf, true)); }
; __device__ __forceinline__ float dpp_shr2(float v) { return __builtin_bit_cast(float, __builtin_amdgcn_update_dpp(0, __builtin_bit_cast(int, v), 0x112, 0xf, 0xf, true)); }
; #define FOR_AI_M _Pragma("unroll") for (int ai = 0; ai < 2; ++ai) _Pragma("unroll") for (int m = 0; m < 4; ++m)
;     __device__ __forceinline__ void operator()(EPI_ARGS) const {
;     ...
;         FOR_AI_M {
;             const int R = ai * 128 + wr * 64 + m * 16 + fr; const int rb = ai * 8 + wr * 4 + m;
;             u32x4 ow;
;             const bool valid = gather ? ((R & 3) >= 2) : (R >= 2);
;             const int orow = gather ? (256 * (R >> 2) + 252 + (R & 3)) : (256 * u.pm + R - 2);
; #pragma unroll
;             for (int n = 0; n < 2; ++n) {
;                 const int cl = wc * 32 + 8 * fq + 4 * n;
;                 f32x4 hA = (f32x4){0.f, 0.f, 0.f, 0.f}, hB = (f32x4){0.f, 0.f, 0.f, 0.f};
;                 if (fr < 2 && rb > 0) { hA = *(const LAS f32x4*)(halo + (((rb - 1) * 2 + fr) * 128 + cl)); if (fr == 0) hB = *(const LAS f32x4*)(halo + (((rb - 1) * 2 + 1) * 128 + cl)); }
;                 const f32x4 g0 = acc[ai][0][m][n], vv = acc[ai][1][m][n];
;                 f32x4 d1, d2;
; #pragma unroll
;                 for (int e = 0; e < 4; ++e) { d1[e] = dpp_shr1(g0[e]); d2[e] = dpp_shr2(g0[e]); }
;                 const f32x4 g1 = d1 + hB, g2 = d2 + hA;
;                 const f32x4 cv = W0[n] * g2 + (W1[n] * g1 + (W2[n] * g0 + BB[n]));
;                 const f32x4 tt = cv * -1.4426950408889634f; f32x4 den;
; #pragma unroll
;                 for (int e = 0; e < 4; ++e) den[e] = __builtin_amdgcn_exp2f(tt[e]);
;                 den = den + 1.0f; f32x4 rc;
; #pragma unroll
;                 for (int e = 0; e < 4; ++e) rc[e] = __builtin_amdgcn_rcpf(den[e]);
;                 const f32x4 o = (cv * rc) * vv;
;                 const u32x2 pk = pack4(o); if (n == 0) { ow.x = pk.x; ow.y = pk.y; } else { ow.z = pk.x; ow.w = pk.y; }
;             }
;             if (valid) *(u32x4*)(ACT + ((size_t)orow * DFF + u.pn * 128 + wc * 32 + 8 * fq)) = ow;
.LBB0_1121:
	s_waitcnt lgkmcnt(0)
	v_mov_b32_dpp v168, v66 row_ror:1 row_mask:0xf bank_mask:0xf
	v_mov_b32_dpp v169, v67 row_ror:1 row_mask:0xf bank_mask:0xf
	s_nop 0
	v_mov_b32_dpp v168, v122 row_shr:1 row_mask:0xf bank_mask:0xf
	v_mov_b32_dpp v169, v123 row_shr:1 row_mask:0xf bank_mask:0xf
	v_mov_b32_dpp v166, v64 row_ror:1 row_mask:0xf bank_mask:0xf
	v_mov_b32_dpp v167, v65 row_ror:1 row_mask:0xf bank_mask:0xf
	s_nop 0
	v_mov_b32_dpp v166, v120 row_shr:1 row_mask:0xf bank_mask:0xf
	v_mov_b32_dpp v167, v121 row_shr:1 row_mask:0xf bank_mask:0xf
	v_mov_b32_dpp v162, v64 row_ror:2 row_mask:0xf bank_mask:0xf
	v_mov_b32_dpp v163, v65 row_ror:2 row_mask:0xf bank_mask:0xf
	s_nop 0
	v_mov_b32_dpp v162, v120 row_shr:2 row_mask:0xf bank_mask:0xf
	v_mov_b32_dpp v163, v121 row_shr:2 row_mask:0xf bank_mask:0xf
	v_pk_fma_f32 v[208:209], v[154:155], v[122:123], v[158:159]
	v_pk_fma_f32 v[224:225], v[152:153], v[120:121], v[156:157]
	v_mov_b32_dpp v164, v66 row_ror:2 row_mask:0xf bank_mask:0xf
	v_mov_b32_dpp v165, v67 row_ror:2 row_mask:0xf bank_mask:0xf
	s_nop 0
	v_mov_b32_dpp v164, v122 row_shr:2 row_mask:0xf bank_mask:0xf
	v_mov_b32_dpp v165, v123 row_shr:2 row_mask:0xf bank_mask:0xf
	v_pk_fma_f32 v[166:167], v[148:149], v[166:167], v[224:225]
	v_pk_fma_f32 v[168:169], v[150:151], v[168:169], v[208:209]
	v_pk_fma_f32 v[162:163], v[144:145], v[162:163], v[166:167]
	v_pk_fma_f32 v[164:165], v[146:147], v[164:165], v[168:169]
	v_mul_f32_e32 v161, 0xbfb8aa3b, v162
	v_mul_f32_e32 v167, 0xbfb8aa3b, v164
	v_exp_f32_e32 v166, v161
	v_mul_f32_e32 v161, 0xbfb8aa3b, v163
	v_exp_f32_e32 v168, v167
	v_mul_f32_e32 v167, 0xbfb8aa3b, v165
	v_exp_f32_e32 v169, v167
	v_exp_f32_e32 v167, v161
	v_mov_b32_e32 v207, v206
	v_mov_b32_e32 v208, v206
	v_pk_add_f32 v[168:169], v[168:169], 1.0 op_sel_hi:[1,0]
	v_pk_add_f32 v[166:167], v[166:167], 1.0 op_sel_hi:[1,0]
	v_rcp_f32_e32 v168, v168
	v_rcp_f32_e32 v166, v166
	v_rcp_f32_e32 v167, v167
	v_rcp_f32_e32 v169, v169
	v_mov_b32_e32 v209, v206
	v_pk_mul_f32 v[90:91], v[90:91], v[208:209]
	v_pk_mul_f32 v[88:89], v[88:89], v[206:207]
	v_pk_mul_f32 v[162:163], v[162:163], v[166:167]
	v_pk_mul_f32 v[164:165], v[164:165], v[168:169]
	v_pk_mul_f32 v[162:163], v[88:89], v[162:163]
	v_pk_mul_f32 v[166:167], v[90:91], v[164:165]
	v_cvt_pk_bf16_f32 v164, v162, v163
	v_mov_b32_e32 v161, 0
	v_cvt_pk_bf16_f32 v165, v166, v167
	v_mov_b32_e32 v162, 0
	v_mov_b32_e32 v163, 0
	v_mov_b32_e32 v166, 0
	v_mov_b32_e32 v167, 0
	v_mov_b32_e32 v168, 0
	v_mov_b32_e32 v169, 0
.LBB0_1125:
	v_pk_mul_f32 v[86:87], v[86:87], v[208:209]
	v_pk_mul_f32 v[84:85], v[84:85], v[206:207]
	s_waitcnt lgkmcnt(0)
	v_mov_b32_dpp v166, v124 row_ror:1 row_mask:0xf bank_mask:0xf
	v_mov_b32_dpp v167, v125 row_ror:1 row_mask:0xf bank_mask:0xf
	s_nop 0
	v_mov_b32_dpp v166, v116 row_shr:1 row_mask:0xf bank_mask:0xf
	v_mov_b32_dpp v167, v117 row_shr:1 row_mask:0xf bank_mask:0xf
	v_mov_b32_dpp v160, v124 row_ror:2 row_mask:0xf bank_mask:0xf
	v_mov_b32_dpp v161, v125 row_ror:2 row_mask:0xf bank_mask:0xf
	s_nop 0
	v_mov_b32_dpp v160, v116 row_shr:2 row_mask:0xf bank_mask:0xf
	v_mov_b32_dpp v161, v117 row_shr:2 row_mask:0xf bank_mask:0xf
	v_pk_fma_f32 v[208:209], v[116:117], v[136:137], v[140:141]
	v_pk_fma_f32 v[166:167], v[132:133], v[166:167], v[208:209]
	v_pk_fma_f32 v[160:161], v[128:129], v[160:161], v[166:167]
	v_mul_f32_e32 v166, 0xbfb8aa3b, v160
	v_mul_f32_e32 v167, 0xbfb8aa3b, v161
	v_exp_f32_e32 v166, v166
	v_exp_f32_e32 v167, v167
	v_mov_b32_dpp v168, v126 row_ror:1 row_mask:0xf bank_mask:0xf
	v_mov_b32_dpp v169, v127 row_ror:1 row_mask:0xf bank_mask:0xf
	s_nop 0
	v_mov_b32_dpp v168, v118 row_shr:1 row_mask:0xf bank_mask:0xf
	v_mov_b32_dpp v169, v119 row_shr:1 row_mask:0xf bank_mask:0xf
	v_pk_fma_f32 v[206:207], v[118:119], v[138:139], v[142:143]
	v_mov_b32_dpp v162, v126 row_ror:2 row_mask:0xf bank_mask:0xf
	v_mov_b32_dpp v163, v127 row_ror:2 row_mask:0xf bank_mask:0xf
	s_nop 0
	v_mov_b32_dpp v162, v118 row_shr:2 row_mask:0xf bank_mask:0xf
	v_mov_b32_dpp v163, v119 row_shr:2 row_mask:0xf bank_mask:0xf
	v_pk_fma_f32 v[168:169], v[134:135], v[168:169], v[206:207]
	v_pk_add_f32 v[166:167], v[166:167], 1.0 op_sel_hi:[1,0]
	v_pk_fma_f32 v[162:163], v[130:131], v[162:163], v[168:169]
	v_rcp_f32_e32 v166, v166
	v_mul_f32_e32 v168, 0xbfb8aa3b, v162
	v_mul_f32_e32 v169, 0xbfb8aa3b, v163
	v_exp_f32_e32 v168, v168
	v_exp_f32_e32 v169, v169
	v_rcp_f32_e32 v167, v167
	v_add_u32_e32 v199, 16, v222
	v_cmp_lt_i32_e64 s[50:51], 1, v199
	v_pk_add_f32 v[168:169], v[168:169], 1.0 op_sel_hi:[1,0]
	v_pk_mul_f32 v[160:161], v[160:161], v[166:167]
	v_rcp_f32_e32 v168, v168
	v_rcp_f32_e32 v169, v169
	v_pk_mul_f32 v[160:161], v[84:85], v[160:161]
	v_cndmask_b32_e64 v208, 0, 1, s[48:49]
	v_cvt_pk_bf16_f32 v166, v160, v161
	v_cndmask_b32_e64 v160, 0, 1, s[50:51]
	v_cndmask_b32_e64 v160, v160, v208, s[44:45]
	v_and_b32_e32 v160, 1, v160
	v_pk_mul_f32 v[162:163], v[162:163], v[168:169]
	v_cmp_eq_u32_e64 s[48:49], 1, v160
	v_pk_mul_f32 v[162:163], v[86:87], v[162:163]
	s_nop 0
	v_cvt_pk_bf16_f32 v167, v162, v163
	s_and_saveexec_b64 s[8:9], s[48:49]
	s_cbranch_execz .LBB0_1127
	v_lshlrev_b32_e32 v160, 6, v199
	v_add_u32_e32 v161, s29, v199
	v_or3_b32 v160, v160, v191, s74
	v_cndmask_b32_e64 v162, v161, v160, s[44:45]
	v_mov_b64_e32 v[160:161], s[0:1]
	v_mad_i64_i32 v[160:161], s[48:49], v162, s75, v[160:161]
	v_lshl_add_u64 v[160:161], s[10:11], 1, v[160:161]
	v_lshl_add_u64 v[160:161], s[6:7], 1, v[160:161]
	v_lshl_add_u64 v[160:161], v[192:193], 1, v[160:161]
	global_store_dwordx4 v[160:161], v[164:167], off

; #define LAS __attribute__((address_space(3)))
; __device__ __forceinline__ u32x2 pack4(f32x4 v) { u32x2 r; r.x = cvt_pk(v[0], v[1]); r.y = cvt_pk(v[2], v[3]); return r; }
; __device__ __forceinline__ float dpp_shr1(float v) { return __builtin_bit_cast(float, __builtin_amdgcn_update_dpp(0, __builtin_bit_cast(int, v), 0x111, 0xf, 0xf, true)); }
; __device__ __forceinline__ float dpp_shr2(float v) { return __builtin_bit_cast(float, __builtin_amdgcn_update_dpp(0, __builtin_bit_cast(int, v), 0x112, 0xf, 0xf, true)); }
; #define FOR_AI_M _Pragma("unroll") for (int ai = 0; ai < 2; ++ai) _Pragma("unroll") for (int m = 0; m < 4; ++m)
;     __device__ __forceinline__ void operator()(EPI_ARGS) const {
;     ...
;         FOR_AI_M {
;             const int R = ai * 128 + wr * 64 + m * 16 + fr; const int rb = ai * 8 + wr * 4 + m;
;             u32x4 ow;
;             const bool valid = gather ? ((R & 3) >= 2) : (R >= 2);
;             const int orow = gather ? (256 * (R >> 2) + 252 + (R & 3)) : (256 * u.pm + R - 2);
; #pragma unroll
;             for (int n = 0; n < 2; ++n) {
;                 const int cl = wc * 32 + 8 * fq + 4 * n;
;                 f32x4 hA = (f32x4){0.f, 0.f, 0.f, 0.f}, hB = (f32x4){0.f, 0.f, 0.f, 0.f};
;                 if (fr < 2 && rb > 0) { hA = *(const LAS f32x4*)(halo + (((rb - 1) * 2 + fr) * 128 + cl)); if (fr == 0) hB = *(const LAS f32x4*)(halo + (((rb - 1) * 2 + 1) * 128 + cl)); }
;                 const f32x4 g0 = acc[ai][0][m][n], vv = acc[ai][1][m][n];
;                 f32x4 d1, d2;
; #pragma unroll
;                 for (int e = 0; e < 4; ++e) { d1[e] = dpp_shr1(g0[e]); d2[e] = dpp_shr2(g0[e]); }
;                 const f32x4 g1 = d1 + hB, g2 = d2 + hA;
;                 const f32x4 cv = W0[n] * g2 + (W1[n] * g1 + (W2[n] * g0 + BB[n]));
;                 const f32x4 tt = cv * -1.4426950408889634f; f32x4 den;
; #pragma unroll
;                 for (int e = 0; e < 4; ++e) den[e] = __builtin_amdgcn_exp2f(tt[e]);
;                 den = den + 1.0f; f32x4 rc;
; #pragma unroll
;                 for (int e = 0; e < 4; ++e) rc[e] = __builtin_amdgcn_rcpf(den[e]);
;                 const f32x4 o = (cv * rc) * vv;
;                 const u32x2 pk = pack4(o); if (n == 0) { ow.x = pk.x; ow.y = pk.y; } else { ow.z = pk.x; ow.w = pk.y; }
;             }
;             if (valid) *(u32x4*)(ACT + ((size_t)orow * DFF + u.pn * 128 + wc * 32 + 8 * fq)) = ow;
.LBB0_1131:
	s_waitcnt lgkmcnt(0)
	v_mov_b32_dpp v168, v122 row_ror:1 row_mask:0xf bank_mask:0xf
	v_mov_b32_dpp v169, v123 row_ror:1 row_mask:0xf bank_mask:0xf
	s_nop 0
	v_mov_b32_dpp v168, v114 row_shr:1 row_mask:0xf bank_mask:0xf
	v_mov_b32_dpp v169, v115 row_shr:1 row_mask:0xf bank_mask:0xf
	v_mov_b32_dpp v166, v120 row_ror:1 row_mask:0xf bank_mask:0xf
	v_mov_b32_dpp v167, v121 row_ror:1 row_mask:0xf bank_mask:0xf
	s_nop 0
	v_mov_b32_dpp v166, v112 row_shr:1 row_mask:0xf bank_mask:0xf
	v_mov_b32_dpp v167, v113 row_shr:1 row_mask:0xf bank_mask:0xf
	v_mov_b32_dpp v162, v120 row_ror:2 row_mask:0xf bank_mask:0xf
	v_mov_b32_dpp v163, v121 row_ror:2 row_mask:0xf bank_mask:0xf
	s_nop 0
	v_mov_b32_dpp v162, v112 row_shr:2 row_mask:0xf bank_mask:0xf
	v_mov_b32_dpp v163, v113 row_shr:2 row_mask:0xf bank_mask:0xf
	v_pk_fma_f32 v[206:207], v[154:155], v[114:115], v[158:159]
	v_pk_fma_f32 v[224:225], v[152:153], v[112:113], v[156:157]
	v_mov_b32_dpp v164, v122 row_ror:2 row_mask:0xf bank_mask:0xf
	v_mov_b32_dpp v165, v123 row_ror:2 row_mask:0xf bank_mask:0xf
	s_nop 0
	v_mov_b32_dpp v164, v114 row_shr:2 row_mask:0xf bank_mask:0xf
	v_mov_b32_dpp v165, v115 row_shr:2 row_mask:0xf bank_mask:0xf
	v_pk_fma_f32 v[166:167], v[148:149], v[166:167], v[224:225]
	v_pk_fma_f32 v[168:169], v[150:151], v[168:169], v[206:207]
	v_pk_fma_f32 v[162:163], v[144:145], v[162:163], v[166:167]
	v_pk_fma_f32 v[164:165], v[146:147], v[164:165], v[168:169]
	v_mul_f32_e32 v161, 0xbfb8aa3b, v162
	v_mul_f32_e32 v167, 0xbfb8aa3b, v164
	v_exp_f32_e32 v166, v161
	v_mul_f32_e32 v161, 0xbfb8aa3b, v163
	v_exp_f32_e32 v168, v167
	v_mul_f32_e32 v167, 0xbfb8aa3b, v165
	v_exp_f32_e32 v169, v167
	v_exp_f32_e32 v167, v161
	v_mov_b32_e32 v205, v204
	v_mov_b32_e32 v206, v204
	v_pk_add_f32 v[168:169], v[168:169], 1.0 op_sel_hi:[1,0]
	v_pk_add_f32 v[166:167], v[166:167], 1.0 op_sel_hi:[1,0]
	v_rcp_f32_e32 v168, v168
	v_rcp_f32_e32 v166, v166
	v_rcp_f32_e32 v167, v167
	v_rcp_f32_e32 v169, v169
	v_mov_b32_e32 v207, v204
	v_pk_mul_f32 v[82:83], v[82:83], v[206:207]
	v_pk_mul_f32 v[80:81], v[80:81], v[204:205]
	v_pk_mul_f32 v[162:163], v[162:163], v[166:167]
	v_pk_mul_f32 v[164:165], v[164:165], v[168:169]
	v_pk_mul_f32 v[162:163], v[80:81], v[162:163]
	v_pk_mul_f32 v[166:167], v[82:83], v[164:165]
	v_cvt_pk_bf16_f32 v164, v162, v163
	v_mov_b32_e32 v161, 0
	v_cvt_pk_bf16_f32 v165, v166, v167
	v_mov_b32_e32 v162, 0
	v_mov_b32_e32 v163, 0
	v_mov_b32_e32 v166, 0
	v_mov_b32_e32 v167, 0
	v_mov_b32_e32 v168, 0
	v_mov_b32_e32 v169, 0
.LBB0_1135:
	v_pk_mul_f32 v[78:79], v[78:79], v[206:207]
	v_pk_mul_f32 v[76:77], v[76:77], v[204:205]
	s_waitcnt lgkmcnt(0)
	v_mov_b32_dpp v166, v116 row_ror:1 row_mask:0xf bank_mask:0xf
	v_mov_b32_dpp v167, v117 row_ror:1 row_mask:0xf bank_mask:0xf
	s_nop 0
	v_mov_b32_dpp v166, v108 row_shr:1 row_mask:0xf bank_mask:0xf
	v_mov_b32_dpp v167, v109 row_shr:1 row_mask:0xf bank_mask:0xf
	v_mov_b32_dpp v160, v116 row_ror:2 row_mask:0xf bank_mask:0xf
	v_mov_b32_dpp v161, v117 row_ror:2 row_mask:0xf bank_mask:0xf
	s_nop 0
	v_mov_b32_dpp v160, v108 row_shr:2 row_mask:0xf bank_mask:0xf
	v_mov_b32_dpp v161, v109 row_shr:2 row_mask:0xf bank_mask:0xf
	v_pk_fma_f32 v[206:207], v[108:109], v[136:137], v[140:141]
	v_pk_fma_f32 v[166:167], v[132:133], v[166:167], v[206:207]
	v_pk_fma_f32 v[160:161], v[128:129], v[160:161], v[166:167]
	v_mul_f32_e32 v166, 0xbfb8aa3b, v160
	v_mul_f32_e32 v167, 0xbfb8aa3b, v161
	v_exp_f32_e32 v166, v166
	v_exp_f32_e32 v167, v167
	v_mov_b32_dpp v168, v118 row_ror:1 row_mask:0xf bank_mask:0xf
	v_mov_b32_dpp v169, v119 row_ror:1 row_mask:0xf bank_mask:0xf
	s_nop 0
	v_mov_b32_dpp v168, v110 row_shr:1 row_mask:0xf bank_mask:0xf
	v_mov_b32_dpp v169, v111 row_shr:1 row_mask:0xf bank_mask:0xf
	v_pk_fma_f32 v[204:205], v[110:111], v[138:139], v[142:143]
	v_mov_b32_dpp v162, v118 row_ror:2 row_mask:0xf bank_mask:0xf
	v_mov_b32_dpp v163, v119 row_ror:2 row_mask:0xf bank_mask:0xf
	s_nop 0
	v_mov_b32_dpp v162, v110 row_shr:2 row_mask:0xf bank_mask:0xf
	v_mov_b32_dpp v163, v111 row_shr:2 row_mask:0xf bank_mask:0xf
	v_pk_fma_f32 v[168:169], v[134:135], v[168:169], v[204:205]
	v_pk_add_f32 v[166:167], v[166:167], 1.0 op_sel_hi:[1,0]
	v_pk_fma_f32 v[162:163], v[130:131], v[162:163], v[168:169]
	v_rcp_f32_e32 v166, v166
	v_mul_f32_e32 v168, 0xbfb8aa3b, v162
	v_mul_f32_e32 v169, 0xbfb8aa3b, v163
	v_exp_f32_e32 v168, v168
	v_exp_f32_e32 v169, v169
	v_rcp_f32_e32 v167, v167
	v_add_u32_e32 v199, 32, v222
	v_cmp_lt_i32_e64 s[48:49], 1, v199
	v_pk_add_f32 v[168:169], v[168:169], 1.0 op_sel_hi:[1,0]
	v_pk_mul_f32 v[160:161], v[160:161], v[166:167]
	v_rcp_f32_e32 v168, v168
	v_rcp_f32_e32 v169, v169
	v_pk_mul_f32 v[160:161], v[76:77], v[160:161]
	v_pk_mul_f32 v[162:163], v[162:163], v[168:169]
	v_cvt_pk_bf16_f32 v166, v160, v161
	v_cndmask_b32_e64 v160, 0, 1, s[48:49]
	v_cndmask_b32_e64 v160, v160, v208, s[44:45]
	v_and_b32_e32 v160, 1, v160
	v_cmp_eq_u32_e64 s[48:49], 1, v160
	v_pk_mul_f32 v[162:163], v[78:79], v[162:163]
	s_nop 0
	v_cvt_pk_bf16_f32 v167, v162, v163
	s_and_saveexec_b64 s[8:9], s[48:49]
	s_cbranch_execz .LBB0_1137
	v_lshlrev_b32_e32 v160, 6, v199
	v_add_u32_e32 v161, s29, v199
	v_or3_b32 v160, v160, v191, s74
	v_cndmask_b32_e64 v162, v161, v160, s[44:45]
	v_mov_b64_e32 v[160:161], s[0:1]
	v_mad_i64_i32 v[160:161], s[48:49], v162, s75, v[160:161]
	v_lshl_add_u64 v[160:161], s[10:11], 1, v[160:161]
	v_lshl_add_u64 v[160:161], s[6:7], 1, v[160:161]
	v_lshl_add_u64 v[160:161], v[192:193], 1, v[160:161]
	global_store_dwordx4 v[160:161], v[164:167], off

; #define LAS __attribute__((address_space(3)))
; __device__ __forceinline__ u32x2 pack4(f32x4 v) { u32x2 r; r.x = cvt_pk(v[0], v[1]); r.y = cvt_pk(v[2], v[3]); return r; }
; __device__ __forceinline__ float dpp_shr1(float v) { return __builtin_bit_cast(float, __builtin_amdgcn_update_dpp(0, __builtin_bit_cast(int, v), 0x111, 0xf, 0xf, true)); }
; __device__ __forceinline__ float dpp_shr2(float v) { return __builtin_bit_cast(float, __builtin_amdgcn_update_dpp(0, __builtin_bit_cast(int, v), 0x112, 0xf, 0xf, true)); }
; #define FOR_AI_M _Pragma("unroll") for (int ai = 0; ai < 2; ++ai) _Pragma("unroll") for (int m = 0; m < 4; ++m)
;     __device__ __forceinline__ void operator()(EPI_ARGS) const {
;     ...
;         FOR_AI_M {
;             const int R = ai * 128 + wr * 64 + m * 16 + fr; const int rb = ai * 8 + wr * 4 + m;
;             u32x4 ow;
;             const bool valid = gather ? ((R & 3) >= 2) : (R >= 2);
;             const int orow = gather ? (256 * (R >> 2) + 252 + (R & 3)) : (256 * u.pm + R - 2);
; #pragma unroll
;             for (int n = 0; n < 2; ++n) {
;                 const int cl = wc * 32 + 8 * fq + 4 * n;
;                 f32x4 hA = (f32x4){0.f, 0.f, 0.f, 0.f}, hB = (f32x4){0.f, 0.f, 0.f, 0.f};
;                 if (fr < 2 && rb > 0) { hA = *(const LAS f32x4*)(halo + (((rb - 1) * 2 + fr) * 128 + cl)); if (fr == 0) hB = *(const LAS f32x4*)(halo + (((rb - 1) * 2 + 1) * 128 + cl)); }
;                 const f32x4 g0 = acc[ai][0][m][n], vv = acc[ai][1][m][n];
;                 f32x4 d1, d2;
; #pragma unroll
;                 for (int e = 0; e < 4; ++e) { d1[e] = dpp_shr1(g0[e]); d2[e] = dpp_shr2(g0[e]); }
;                 const f32x4 g1 = d1 + hB, g2 = d2 + hA;
;                 const f32x4 cv = W0[n] * g2 + (W1[n] * g1 + (W2[n] * g0 + BB[n]));
;                 const f32x4 tt = cv * -1.4426950408889634f; f32x4 den;
; #pragma unroll
;                 for (int e = 0; e < 4; ++e) den[e] = __builtin_amdgcn_exp2f(tt[e]);
;                 den = den + 1.0f; f32x4 rc;
; #pragma unroll
;                 for (int e = 0; e < 4; ++e) rc[e] = __builtin_amdgcn_rcpf(den[e]);
;                 const f32x4 o = (cv * rc) * vv;
;                 const u32x2 pk = pack4(o); if (n == 0) { ow.x = pk.x; ow.y = pk.y; } else { ow.z = pk.x; ow.w = pk.y; }
;             }
;             if (valid) *(u32x4*)(ACT + ((size_t)orow * DFF + u.pn * 128 + wc * 32 + 8 * fq)) = ow;
.LBB0_1141:
	s_waitcnt lgkmcnt(0)
	v_mov_b32_dpp v168, v114 row_ror:1 row_mask:0xf bank_mask:0xf
	v_mov_b32_dpp v169, v115 row_ror:1 row_mask:0xf bank_mask:0xf
	s_nop 0
	v_mov_b32_dpp v168, v106 row_shr:1 row_mask:0xf bank_mask:0xf
	v_mov_b32_dpp v169, v107 row_shr:1 row_mask:0xf bank_mask:0xf
	v_mov_b32_dpp v166, v112 row_ror:1 row_mask:0xf bank_mask:0xf
	v_mov_b32_dpp v167, v113 row_ror:1 row_mask:0xf bank_mask:0xf
	s_nop 0
	v_mov_b32_dpp v166, v104 row_shr:1 row_mask:0xf bank_mask:0xf
	v_mov_b32_dpp v167, v105 row_shr:1 row_mask:0xf bank_mask:0xf
	v_mov_b32_dpp v162, v112 row_ror:2 row_mask:0xf bank_mask:0xf
	v_mov_b32_dpp v163, v113 row_ror:2 row_mask:0xf bank_mask:0xf
	s_nop 0
	v_mov_b32_dpp v162, v104 row_shr:2 row_mask:0xf bank_mask:0xf
	v_mov_b32_dpp v163, v105 row_shr:2 row_mask:0xf bank_mask:0xf
	v_pk_fma_f32 v[204:205], v[154:155], v[106:107], v[158:159]
	v_pk_fma_f32 v[206:207], v[152:153], v[104:105], v[156:157]
	v_mov_b32_dpp v164, v114 row_ror:2 row_mask:0xf bank_mask:0xf
	v_mov_b32_dpp v165, v115 row_ror:2 row_mask:0xf bank_mask:0xf
	s_nop 0
	v_mov_b32_dpp v164, v106 row_shr:2 row_mask:0xf bank_mask:0xf
	v_mov_b32_dpp v165, v107 row_shr:2 row_mask:0xf bank_mask:0xf
	v_pk_fma_f32 v[166:167], v[148:149], v[166:167], v[206:207]
	v_pk_fma_f32 v[168:169], v[150:151], v[168:169], v[204:205]
	v_pk_fma_f32 v[162:163], v[144:145], v[162:163], v[166:167]
	v_pk_fma_f32 v[164:165], v[146:147], v[164:165], v[168:169]
	v_mul_f32_e32 v161, 0xbfb8aa3b, v162
	v_mul_f32_e32 v167, 0xbfb8aa3b, v164
	v_exp_f32_e32 v166, v161
	v_mul_f32_e32 v161, 0xbfb8aa3b, v163
	v_exp_f32_e32 v168, v167
	v_mul_f32_e32 v167, 0xbfb8aa3b, v165
	v_exp_f32_e32 v169, v167
	v_exp_f32_e32 v167, v161
	v_mov_b32_e32 v203, v202
	v_mov_b32_e32 v204, v202
	v_pk_add_f32 v[168:169], v[168:169], 1.0 op_sel_hi:[1,0]
	v_pk_add_f32 v[166:167], v[166:167], 1.0 op_sel_hi:[1,0]
	v_rcp_f32_e32 v168, v168
	v_rcp_f32_e32 v166, v166
	v_rcp_f32_e32 v167, v167
	v_rcp_f32_e32 v169, v169
	v_mov_b32_e32 v205, v202
	v_pk_mul_f32 v[74:75], v[74:75], v[204:205]
	v_pk_mul_f32 v[72:73], v[72:73], v[202:203]
	v_pk_mul_f32 v[162:163], v[162:163], v[166:167]
	v_pk_mul_f32 v[164:165], v[164:165], v[168:169]
	v_pk_mul_f32 v[162:163], v[72:73], v[162:163]
	v_pk_mul_f32 v[166:167], v[74:75], v[164:165]
	v_cvt_pk_bf16_f32 v164, v162, v163
	v_mov_b32_e32 v161, 0
	v_cvt_pk_bf16_f32 v165, v166, v167
	v_mov_b32_e32 v162, 0
	v_mov_b32_e32 v163, 0
	v_mov_b32_e32 v166, 0
	v_mov_b32_e32 v167, 0
	v_mov_b32_e32 v168, 0
	v_mov_b32_e32 v169, 0
.LBB0_1145:
	v_pk_mul_f32 v[70:71], v[70:71], v[204:205]
	v_pk_mul_f32 v[68:69], v[68:69], v[202:203]
	s_waitcnt lgkmcnt(0)
	v_mov_b32_dpp v166, v108 row_ror:1 row_mask:0xf bank_mask:0xf
	v_mov_b32_dpp v167, v109 row_ror:1 row_mask:0xf bank_mask:0xf
	s_nop 0
	v_mov_b32_dpp v166, v100 row_shr:1 row_mask:0xf bank_mask:0xf
	v_mov_b32_dpp v167, v101 row_shr:1 row_mask:0xf bank_mask:0xf
	v_mov_b32_dpp v160, v108 row_ror:2 row_mask:0xf bank_mask:0xf
	v_mov_b32_dpp v161, v109 row_ror:2 row_mask:0xf bank_mask:0xf
	s_nop 0
	v_mov_b32_dpp v160, v100 row_shr:2 row_mask:0xf bank_mask:0xf
	v_mov_b32_dpp v161, v101 row_shr:2 row_mask:0xf bank_mask:0xf
	v_pk_fma_f32 v[204:205], v[100:101], v[136:137], v[140:141]
	v_pk_fma_f32 v[166:167], v[132:133], v[166:167], v[204:205]
	v_pk_fma_f32 v[160:161], v[128:129], v[160:161], v[166:167]
	v_mul_f32_e32 v166, 0xbfb8aa3b, v160
	v_mul_f32_e32 v167, 0xbfb8aa3b, v161
	v_exp_f32_e32 v166, v166
	v_exp_f32_e32 v167, v167
	v_mov_b32_dpp v168, v110 row_ror:1 row_mask:0xf bank_mask:0xf
	v_mov_b32_dpp v169, v111 row_ror:1 row_mask:0xf bank_mask:0xf
	s_nop 0
	v_mov_b32_dpp v168, v102 row_shr:1 row_mask:0xf bank_mask:0xf
	v_mov_b32_dpp v169, v103 row_shr:1 row_mask:0xf bank_mask:0xf
	v_pk_fma_f32 v[202:203], v[102:103], v[138:139], v[142:143]
	v_mov_b32_dpp v162, v110 row_ror:2 row_mask:0xf bank_mask:0xf
	v_mov_b32_dpp v163, v111 row_ror:2 row_mask:0xf bank_mask:0xf
	s_nop 0
	v_mov_b32_dpp v162, v102 row_shr:2 row_mask:0xf bank_mask:0xf
	v_mov_b32_dpp v163, v103 row_shr:2 row_mask:0xf bank_mask:0xf
	v_pk_fma_f32 v[168:169], v[134:135], v[168:169], v[202:203]
	v_pk_add_f32 v[166:167], v[166:167], 1.0 op_sel_hi:[1,0]
	v_pk_fma_f32 v[162:163], v[130:131], v[162:163], v[168:169]
	v_rcp_f32_e32 v166, v166
	v_mul_f32_e32 v168, 0xbfb8aa3b, v162
	v_mul_f32_e32 v169, 0xbfb8aa3b, v163
	v_exp_f32_e32 v168, v168
	v_exp_f32_e32 v169, v169
	v_rcp_f32_e32 v167, v167
	v_add_u32_e32 v199, 48, v222
	v_cmp_lt_i32_e64 s[48:49], 1, v199
	v_pk_add_f32 v[168:169], v[168:169], 1.0 op_sel_hi:[1,0]
	v_pk_mul_f32 v[160:161], v[160:161], v[166:167]
	v_rcp_f32_e32 v168, v168
	v_rcp_f32_e32 v169, v169
	v_pk_mul_f32 v[160:161], v[68:69], v[160:161]
	v_pk_mul_f32 v[162:163], v[162:163], v[168:169]
	v_cvt_pk_bf16_f32 v166, v160, v161
	v_cndmask_b32_e64 v160, 0, 1, s[48:49]
	v_cndmask_b32_e64 v160, v160, v208, s[44:45]
	v_and_b32_e32 v160, 1, v160
	v_cmp_eq_u32_e64 s[48:49], 1, v160
	v_pk_mul_f32 v[162:163], v[70:71], v[162:163]
	s_nop 0
	v_cvt_pk_bf16_f32 v167, v162, v163
	s_and_saveexec_b64 s[8:9], s[48:49]
	s_cbranch_execz .LBB0_1147
	v_lshlrev_b32_e32 v160, 6, v199
	v_add_u32_e32 v161, s29, v199
	v_or3_b32 v160, v160, v191, s74
	v_cndmask_b32_e64 v162, v161, v160, s[44:45]
	v_mov_b64_e32 v[160:161], s[0:1]
	v_mad_i64_i32 v[160:161], s[12:13], v162, s75, v[160:161]
	v_lshl_add_u64 v[160:161], s[10:11], 1, v[160:161]
	v_lshl_add_u64 v[160:161], s[6:7], 1, v[160:161]
	v_lshl_add_u64 v[160:161], v[192:193], 1, v[160:161]
	global_store_dwordx4 v[160:161], v[164:167], off

; #define LAS __attribute__((address_space(3)))
; __device__ __forceinline__ u32x2 pack4(f32x4 v) { u32x2 r; r.x = cvt_pk(v[0], v[1]); r.y = cvt_pk(v[2], v[3]); return r; }
; __device__ __forceinline__ float dpp_shr1(float v) { return __builtin_bit_cast(float, __builtin_amdgcn_update_dpp(0, __builtin_bit_cast(int, v), 0x111, 0xf, 0xf, true)); }
; __device__ __forceinline__ float dpp_shr2(float v) { return __builtin_bit_cast(float, __builtin_amdgcn_update_dpp(0, __builtin_bit_cast(int, v), 0x112, 0xf, 0xf, true)); }
; #define FOR_AI_M _Pragma("unroll") for (int ai = 0; ai < 2; ++ai) _Pragma("unroll") for (int m = 0; m < 4; ++m)
;     __device__ __forceinline__ void operator()(EPI_ARGS) const {
;     ...
;         FOR_AI_M {
;             const int R = ai * 128 + wr * 64 + m * 16 + fr; const int rb = ai * 8 + wr * 4 + m;
;             u32x4 ow;
;             const bool valid = gather ? ((R & 3) >= 2) : (R >= 2);
;             const int orow = gather ? (256 * (R >> 2) + 252 + (R & 3)) : (256 * u.pm + R - 2);
; #pragma unroll
;             for (int n = 0; n < 2; ++n) {
;                 const int cl = wc * 32 + 8 * fq + 4 * n;
;                 f32x4 hA = (f32x4){0.f, 0.f, 0.f, 0.f}, hB = (f32x4){0.f, 0.f, 0.f, 0.f};
;                 if (fr < 2 && rb > 0) { hA = *(const LAS f32x4*)(halo + (((rb - 1) * 2 + fr) * 128 + cl)); if (fr == 0) hB = *(const LAS f32x4*)(halo + (((rb - 1) * 2 + 1) * 128 + cl)); }
;                 const f32x4 g0 = acc[ai][0][m][n], vv = acc[ai][1][m][n];
;                 f32x4 d1, d2;
; #pragma unroll
;                 for (int e = 0; e < 4; ++e) { d1[e] = dpp_shr1(g0[e]); d2[e] = dpp_shr2(g0[e]); }
;                 const f32x4 g1 = d1 + hB, g2 = d2 + hA;
;                 const f32x4 cv = W0[n] * g2 + (W1[n] * g1 + (W2[n] * g0 + BB[n]));
;                 const f32x4 tt = cv * -1.4426950408889634f; f32x4 den;
; #pragma unroll
;                 for (int e = 0; e < 4; ++e) den[e] = __builtin_amdgcn_exp2f(tt[e]);
;                 den = den + 1.0f; f32x4 rc;
; #pragma unroll
;                 for (int e = 0; e < 4; ++e) rc[e] = __builtin_amdgcn_rcpf(den[e]);
;                 const f32x4 o = (cv * rc) * vv;
;                 const u32x2 pk = pack4(o); if (n == 0) { ow.x = pk.x; ow.y = pk.y; } else { ow.z = pk.x; ow.w = pk.y; }
;             }
;             if (valid) *(u32x4*)(ACT + ((size_t)orow * DFF + u.pn * 128 + wc * 32 + 8 * fq)) = ow;
.LBB0_1161:
	s_waitcnt lgkmcnt(0)
	v_mov_b32_dpp v168, v62 row_ror:1 row_mask:0xf bank_mask:0xf
	v_mov_b32_dpp v169, v63 row_ror:1 row_mask:0xf bank_mask:0xf
	s_nop 0
	v_mov_b32_dpp v168, v54 row_shr:1 row_mask:0xf bank_mask:0xf
	v_mov_b32_dpp v169, v55 row_shr:1 row_mask:0xf bank_mask:0xf
	v_mov_b32_dpp v166, v60 row_ror:1 row_mask:0xf bank_mask:0xf
	v_mov_b32_dpp v167, v61 row_ror:1 row_mask:0xf bank_mask:0xf
	s_nop 0
	v_mov_b32_dpp v166, v52 row_shr:1 row_mask:0xf bank_mask:0xf
	v_mov_b32_dpp v167, v53 row_shr:1 row_mask:0xf bank_mask:0xf
	v_mov_b32_dpp v162, v60 row_ror:2 row_mask:0xf bank_mask:0xf
	v_mov_b32_dpp v163, v61 row_ror:2 row_mask:0xf bank_mask:0xf
	s_nop 0
	v_mov_b32_dpp v162, v52 row_shr:2 row_mask:0xf bank_mask:0xf
	v_mov_b32_dpp v163, v53 row_shr:2 row_mask:0xf bank_mask:0xf
	v_pk_fma_f32 v[200:201], v[154:155], v[54:55], v[158:159]
	v_pk_fma_f32 v[202:203], v[152:153], v[52:53], v[156:157]
	v_mov_b32_dpp v164, v62 row_ror:2 row_mask:0xf bank_mask:0xf
	v_mov_b32_dpp v165, v63 row_ror:2 row_mask:0xf bank_mask:0xf
	s_nop 0
	v_mov_b32_dpp v164, v54 row_shr:2 row_mask:0xf bank_mask:0xf
	v_mov_b32_dpp v165, v55 row_shr:2 row_mask:0xf bank_mask:0xf
	v_pk_fma_f32 v[166:167], v[148:149], v[166:167], v[202:203]
	v_pk_fma_f32 v[168:169], v[150:151], v[168:169], v[200:201]
	v_pk_fma_f32 v[162:163], v[144:145], v[162:163], v[166:167]
	v_pk_fma_f32 v[164:165], v[146:147], v[164:165], v[168:169]
	v_mul_f32_e32 v161, 0xbfb8aa3b, v162
	v_mul_f32_e32 v167, 0xbfb8aa3b, v164
	v_exp_f32_e32 v166, v161
	v_mul_f32_e32 v161, 0xbfb8aa3b, v163
	v_exp_f32_e32 v168, v167
	v_mul_f32_e32 v167, 0xbfb8aa3b, v165
	v_exp_f32_e32 v169, v167
	v_exp_f32_e32 v167, v161
	v_mov_b32_e32 v199, v198
	v_mov_b32_e32 v200, v198
	v_pk_add_f32 v[168:169], v[168:169], 1.0 op_sel_hi:[1,0]
	v_pk_add_f32 v[166:167], v[166:167], 1.0 op_sel_hi:[1,0]
	v_rcp_f32_e32 v168, v168
	v_rcp_f32_e32 v166, v166
	v_rcp_f32_e32 v167, v167
	v_rcp_f32_e32 v169, v169
	v_mov_b32_e32 v201, v198
	v_pk_mul_f32 v[22:23], v[22:23], v[200:201]
	v_pk_mul_f32 v[20:21], v[20:21], v[198:199]
	v_pk_mul_f32 v[162:163], v[162:163], v[166:167]
	v_pk_mul_f32 v[164:165], v[164:165], v[168:169]
	v_pk_mul_f32 v[162:163], v[20:21], v[162:163]
	v_pk_mul_f32 v[166:167], v[22:23], v[164:165]
	v_cvt_pk_bf16_f32 v164, v162, v163
	v_mov_b32_e32 v161, 0
	v_cvt_pk_bf16_f32 v165, v166, v167
	v_mov_b32_e32 v162, 0
	v_mov_b32_e32 v163, 0
	v_mov_b32_e32 v166, 0
	v_mov_b32_e32 v167, 0
	v_mov_b32_e32 v168, 0
	v_mov_b32_e32 v169, 0
.LBB0_1165:
	v_pk_mul_f32 v[18:19], v[18:19], v[200:201]
	v_pk_mul_f32 v[16:17], v[16:17], v[198:199]
	s_waitcnt lgkmcnt(0)
	v_mov_b32_dpp v166, v56 row_ror:1 row_mask:0xf bank_mask:0xf
	v_mov_b32_dpp v167, v57 row_ror:1 row_mask:0xf bank_mask:0xf
	s_nop 0
	v_mov_b32_dpp v166, v48 row_shr:1 row_mask:0xf bank_mask:0xf
	v_mov_b32_dpp v167, v49 row_shr:1 row_mask:0xf bank_mask:0xf
	v_mov_b32_dpp v160, v56 row_ror:2 row_mask:0xf bank_mask:0xf
	v_mov_b32_dpp v161, v57 row_ror:2 row_mask:0xf bank_mask:0xf
	s_nop 0
	v_mov_b32_dpp v160, v48 row_shr:2 row_mask:0xf bank_mask:0xf
	v_mov_b32_dpp v161, v49 row_shr:2 row_mask:0xf bank_mask:0xf
	v_pk_fma_f32 v[200:201], v[136:137], v[48:49], v[140:141]
	v_pk_fma_f32 v[166:167], v[132:133], v[166:167], v[200:201]
	v_pk_fma_f32 v[160:161], v[128:129], v[160:161], v[166:167]
	v_mul_f32_e32 v166, 0xbfb8aa3b, v160
	v_mul_f32_e32 v167, 0xbfb8aa3b, v161
	v_exp_f32_e32 v166, v166
	v_exp_f32_e32 v167, v167
	v_mov_b32_dpp v168, v58 row_ror:1 row_mask:0xf bank_mask:0xf
	v_mov_b32_dpp v169, v59 row_ror:1 row_mask:0xf bank_mask:0xf
	s_nop 0
	v_mov_b32_dpp v168, v50 row_shr:1 row_mask:0xf bank_mask:0xf
	v_mov_b32_dpp v169, v51 row_shr:1 row_mask:0xf bank_mask:0xf
	v_pk_fma_f32 v[198:199], v[138:139], v[50:51], v[142:143]
	v_mov_b32_dpp v162, v58 row_ror:2 row_mask:0xf bank_mask:0xf
	v_mov_b32_dpp v163, v59 row_ror:2 row_mask:0xf bank_mask:0xf
	s_nop 0
	v_mov_b32_dpp v162, v50 row_shr:2 row_mask:0xf bank_mask:0xf
	v_mov_b32_dpp v163, v51 row_shr:2 row_mask:0xf bank_mask:0xf
	v_pk_fma_f32 v[168:169], v[134:135], v[168:169], v[198:199]
	v_pk_add_f32 v[166:167], v[166:167], 1.0 op_sel_hi:[1,0]
	v_pk_fma_f32 v[162:163], v[130:131], v[162:163], v[168:169]
	v_rcp_f32_e32 v166, v166
	v_mul_f32_e32 v168, 0xbfb8aa3b, v162
	v_mul_f32_e32 v169, 0xbfb8aa3b, v163
	v_exp_f32_e32 v168, v168
	v_exp_f32_e32 v169, v169
	v_rcp_f32_e32 v167, v167
	v_add_u32_e32 v195, 0x90, v222
	v_cmp_lt_i32_e64 s[46:47], 1, v195
	v_pk_add_f32 v[168:169], v[168:169], 1.0 op_sel_hi:[1,0]
	v_pk_mul_f32 v[160:161], v[160:161], v[166:167]
	v_rcp_f32_e32 v168, v168
	v_rcp_f32_e32 v169, v169
	v_pk_mul_f32 v[160:161], v[16:17], v[160:161]
	v_pk_mul_f32 v[162:163], v[162:163], v[168:169]
	v_cvt_pk_bf16_f32 v166, v160, v161
	v_cndmask_b32_e64 v160, 0, 1, s[46:47]
	v_cndmask_b32_e64 v160, v160, v208, s[44:45]
	v_and_b32_e32 v160, 1, v160
	v_cmp_eq_u32_e64 s[46:47], 1, v160
	v_pk_mul_f32 v[162:163], v[18:19], v[162:163]
	s_nop 0
	v_cvt_pk_bf16_f32 v167, v162, v163
	s_and_saveexec_b64 s[8:9], s[46:47]
	s_cbranch_execz .LBB0_1167
	v_lshlrev_b32_e32 v160, 6, v195
	v_add_u32_e32 v161, s29, v195
	v_or3_b32 v160, v160, v191, s74
	v_cndmask_b32_e64 v162, v161, v160, s[44:45]
	v_mov_b64_e32 v[160:161], s[0:1]
	v_mad_i64_i32 v[160:161], s[46:47], v162, s75, v[160:161]
	v_lshl_add_u64 v[160:161], s[10:11], 1, v[160:161]
	v_lshl_add_u64 v[160:161], s[6:7], 1, v[160:161]
	v_lshl_add_u64 v[160:161], v[192:193], 1, v[160:161]
	global_store_dwordx4 v[160:161], v[164:167], off

; #define LAS __attribute__((address_space(3)))
; __device__ __forceinline__ u32x2 pack4(f32x4 v) { u32x2 r; r.x = cvt_pk(v[0], v[1]); r.y = cvt_pk(v[2], v[3]); return r; }
; __device__ __forceinline__ float dpp_shr1(float v) { return __builtin_bit_cast(float, __builtin_amdgcn_update_dpp(0, __builtin_bit_cast(int, v), 0x111, 0xf, 0xf, true)); }
; __device__ __forceinline__ float dpp_shr2(float v) { return __builtin_bit_cast(float, __builtin_amdgcn_update_dpp(0, __builtin_bit_cast(int, v), 0x112, 0xf, 0xf, true)); }
; #define FOR_AI_M _Pragma("unroll") for (int ai = 0; ai < 2; ++ai) _Pragma("unroll") for (int m = 0; m < 4; ++m)
;     __device__ __forceinline__ void operator()(EPI_ARGS) const {
;     ...
;         FOR_AI_M {
;             const int R = ai * 128 + wr * 64 + m * 16 + fr; const int rb = ai * 8 + wr * 4 + m;
;             u32x4 ow;
;             const bool valid = gather ? ((R & 3) >= 2) : (R >= 2);
;             const int orow = gather ? (256 * (R >> 2) + 252 + (R & 3)) : (256 * u.pm + R - 2);
; #pragma unroll
;             for (int n = 0; n < 2; ++n) {
;                 const int cl = wc * 32 + 8 * fq + 4 * n;
;                 f32x4 hA = (f32x4){0.f, 0.f, 0.f, 0.f}, hB = (f32x4){0.f, 0.f, 0.f, 0.f};
;                 if (fr < 2 && rb > 0) { hA = *(const LAS f32x4*)(halo + (((rb - 1) * 2 + fr) * 128 + cl)); if (fr == 0) hB = *(const LAS f32x4*)(halo + (((rb - 1) * 2 + 1) * 128 + cl)); }
;                 const f32x4 g0 = acc[ai][0][m][n], vv = acc[ai][1][m][n];
;                 f32x4 d1, d2;
; #pragma unroll
;                 for (int e = 0; e < 4; ++e) { d1[e] = dpp_shr1(g0[e]); d2[e] = dpp_shr2(g0[e]); }
;                 const f32x4 g1 = d1 + hB, g2 = d2 + hA;
;                 const f32x4 cv = W0[n] * g2 + (W1[n] * g1 + (W2[n] * g0 + BB[n]));
;                 const f32x4 tt = cv * -1.4426950408889634f; f32x4 den;
; #pragma unroll
;                 for (int e = 0; e < 4; ++e) den[e] = __builtin_amdgcn_exp2f(tt[e]);
;                 den = den + 1.0f; f32x4 rc;
; #pragma unroll
;                 for (int e = 0; e < 4; ++e) rc[e] = __builtin_amdgcn_rcpf(den[e]);
;                 const f32x4 o = (cv * rc) * vv;
;                 const u32x2 pk = pack4(o); if (n == 0) { ow.x = pk.x; ow.y = pk.y; } else { ow.z = pk.x; ow.w = pk.y; }
;             }
;             if (valid) *(u32x4*)(ACT + ((size_t)orow * DFF + u.pn * 128 + wc * 32 + 8 * fq)) = ow;
.LBB0_1171:
	s_waitcnt lgkmcnt(0)
	v_mov_b32_dpp v168, v54 row_ror:1 row_mask:0xf bank_mask:0xf
	v_mov_b32_dpp v169, v55 row_ror:1 row_mask:0xf bank_mask:0xf
	s_nop 0
	v_mov_b32_dpp v168, v46 row_shr:1 row_mask:0xf bank_mask:0xf
	v_mov_b32_dpp v169, v47 row_shr:1 row_mask:0xf bank_mask:0xf
	v_mov_b32_dpp v166, v52 row_ror:1 row_mask:0xf bank_mask:0xf
	v_mov_b32_dpp v167, v53 row_ror:1 row_mask:0xf bank_mask:0xf
	s_nop 0
	v_mov_b32_dpp v166, v44 row_shr:1 row_mask:0xf bank_mask:0xf
	v_mov_b32_dpp v167, v45 row_shr:1 row_mask:0xf bank_mask:0xf
	v_mov_b32_dpp v162, v52 row_ror:2 row_mask:0xf bank_mask:0xf
	v_mov_b32_dpp v163, v53 row_ror:2 row_mask:0xf bank_mask:0xf
	s_nop 0
	v_mov_b32_dpp v162, v44 row_shr:2 row_mask:0xf bank_mask:0xf
	v_mov_b32_dpp v163, v45 row_shr:2 row_mask:0xf bank_mask:0xf
	v_pk_fma_f32 v[198:199], v[154:155], v[46:47], v[158:159]
	v_pk_fma_f32 v[200:201], v[152:153], v[44:45], v[156:157]
	v_mov_b32_dpp v164, v54 row_ror:2 row_mask:0xf bank_mask:0xf
	v_mov_b32_dpp v165, v55 row_ror:2 row_mask:0xf bank_mask:0xf
	s_nop 0
	v_mov_b32_dpp v164, v46 row_shr:2 row_mask:0xf bank_mask:0xf
	v_mov_b32_dpp v165, v47 row_shr:2 row_mask:0xf bank_mask:0xf
	v_pk_fma_f32 v[166:167], v[148:149], v[166:167], v[200:201]
	v_pk_fma_f32 v[168:169], v[150:151], v[168:169], v[198:199]
	v_pk_fma_f32 v[162:163], v[144:145], v[162:163], v[166:167]
	v_pk_fma_f32 v[164:165], v[146:147], v[164:165], v[168:169]
	v_mul_f32_e32 v161, 0xbfb8aa3b, v162
	v_mul_f32_e32 v167, 0xbfb8aa3b, v164
	v_exp_f32_e32 v166, v161
	v_mul_f32_e32 v161, 0xbfb8aa3b, v163
	v_exp_f32_e32 v168, v167
	v_mul_f32_e32 v167, 0xbfb8aa3b, v165
	v_exp_f32_e32 v169, v167
	v_exp_f32_e32 v167, v161
	v_mov_b32_e32 v197, v196
	v_mov_b32_e32 v198, v196
	v_pk_add_f32 v[168:169], v[168:169], 1.0 op_sel_hi:[1,0]
	v_pk_add_f32 v[166:167], v[166:167], 1.0 op_sel_hi:[1,0]
	v_rcp_f32_e32 v168, v168
	v_rcp_f32_e32 v166, v166
	v_rcp_f32_e32 v167, v167
	v_rcp_f32_e32 v169, v169
	v_mov_b32_e32 v199, v196
	v_pk_mul_f32 v[14:15], v[14:15], v[198:199]
	v_pk_mul_f32 v[12:13], v[12:13], v[196:197]
	v_pk_mul_f32 v[162:163], v[162:163], v[166:167]
	v_pk_mul_f32 v[164:165], v[164:165], v[168:169]
	v_pk_mul_f32 v[162:163], v[12:13], v[162:163]
	v_pk_mul_f32 v[166:167], v[14:15], v[164:165]
	v_cvt_pk_bf16_f32 v164, v162, v163
	v_mov_b32_e32 v161, 0
	v_cvt_pk_bf16_f32 v165, v166, v167
	v_mov_b32_e32 v162, 0
	v_mov_b32_e32 v163, 0
	v_mov_b32_e32 v166, 0
	v_mov_b32_e32 v167, 0
	v_mov_b32_e32 v168, 0
	v_mov_b32_e32 v169, 0
.LBB0_1175:
	v_pk_mul_f32 v[10:11], v[10:11], v[198:199]
	v_pk_mul_f32 v[8:9], v[8:9], v[196:197]
	s_waitcnt lgkmcnt(0)
	v_mov_b32_dpp v166, v48 row_ror:1 row_mask:0xf bank_mask:0xf
	v_mov_b32_dpp v167, v49 row_ror:1 row_mask:0xf bank_mask:0xf
	s_nop 0
	v_mov_b32_dpp v166, v40 row_shr:1 row_mask:0xf bank_mask:0xf
	v_mov_b32_dpp v167, v41 row_shr:1 row_mask:0xf bank_mask:0xf
	v_mov_b32_dpp v160, v48 row_ror:2 row_mask:0xf bank_mask:0xf
	v_mov_b32_dpp v161, v49 row_ror:2 row_mask:0xf bank_mask:0xf
	s_nop 0
	v_mov_b32_dpp v160, v40 row_shr:2 row_mask:0xf bank_mask:0xf
	v_mov_b32_dpp v161, v41 row_shr:2 row_mask:0xf bank_mask:0xf
	v_pk_fma_f32 v[198:199], v[136:137], v[40:41], v[140:141]
	v_pk_fma_f32 v[166:167], v[132:133], v[166:167], v[198:199]
	v_pk_fma_f32 v[160:161], v[128:129], v[160:161], v[166:167]
	v_mul_f32_e32 v166, 0xbfb8aa3b, v160
	v_mul_f32_e32 v167, 0xbfb8aa3b, v161
	v_exp_f32_e32 v166, v166
	v_exp_f32_e32 v167, v167
	v_mov_b32_dpp v168, v50 row_ror:1 row_mask:0xf bank_mask:0xf
	v_mov_b32_dpp v169, v51 row_ror:1 row_mask:0xf bank_mask:0xf
	s_nop 0
	v_mov_b32_dpp v168, v42 row_shr:1 row_mask:0xf bank_mask:0xf
	v_mov_b32_dpp v169, v43 row_shr:1 row_mask:0xf bank_mask:0xf
	v_pk_fma_f32 v[196:197], v[138:139], v[42:43], v[142:143]
	v_mov_b32_dpp v162, v50 row_ror:2 row_mask:0xf bank_mask:0xf
	v_mov_b32_dpp v163, v51 row_ror:2 row_mask:0xf bank_mask:0xf
	s_nop 0
	v_mov_b32_dpp v162, v42 row_shr:2 row_mask:0xf bank_mask:0xf
	v_mov_b32_dpp v163, v43 row_shr:2 row_mask:0xf bank_mask:0xf
	v_pk_fma_f32 v[168:169], v[134:135], v[168:169], v[196:197]
	v_pk_add_f32 v[166:167], v[166:167], 1.0 op_sel_hi:[1,0]
	v_pk_fma_f32 v[162:163], v[130:131], v[162:163], v[168:169]
	v_rcp_f32_e32 v166, v166
	v_mul_f32_e32 v168, 0xbfb8aa3b, v162
	v_mul_f32_e32 v169, 0xbfb8aa3b, v163
	v_exp_f32_e32 v168, v168
	v_exp_f32_e32 v169, v169
	v_rcp_f32_e32 v167, v167
	v_add_u32_e32 v195, 0xa0, v222
	v_cmp_lt_i32_e64 s[46:47], 1, v195
	v_pk_add_f32 v[168:169], v[168:169], 1.0 op_sel_hi:[1,0]
	v_pk_mul_f32 v[160:161], v[160:161], v[166:167]
	v_rcp_f32_e32 v168, v168
	v_rcp_f32_e32 v169, v169
	v_pk_mul_f32 v[160:161], v[8:9], v[160:161]
	v_pk_mul_f32 v[162:163], v[162:163], v[168:169]
	v_cvt_pk_bf16_f32 v166, v160, v161
	v_cndmask_b32_e64 v160, 0, 1, s[46:47]
	v_cndmask_b32_e64 v160, v160, v208, s[44:45]
	v_and_b32_e32 v160, 1, v160
	v_cmp_eq_u32_e64 s[46:47], 1, v160
	v_pk_mul_f32 v[162:163], v[10:11], v[162:163]
	s_nop 0
	v_cvt_pk_bf16_f32 v167, v162, v163
	s_and_saveexec_b64 s[8:9], s[46:47]
	s_cbranch_execz .LBB0_1177
	v_lshlrev_b32_e32 v160, 6, v195
	v_add_u32_e32 v161, s29, v195
	v_or3_b32 v160, v160, v191, s74
	v_cndmask_b32_e64 v162, v161, v160, s[44:45]
	v_mov_b64_e32 v[160:161], s[0:1]
	v_mad_i64_i32 v[160:161], s[46:47], v162, s75, v[160:161]
	v_lshl_add_u64 v[160:161], s[10:11], 1, v[160:161]
	v_lshl_add_u64 v[160:161], s[6:7], 1, v[160:161]
	v_lshl_add_u64 v[160:161], v[192:193], 1, v[160:161]
	global_store_dwordx4 v[160:161], v[164:167], off

; #define LAS __attribute__((address_space(3)))
; __device__ __forceinline__ u32x2 pack4(f32x4 v) { u32x2 r; r.x = cvt_pk(v[0], v[1]); r.y = cvt_pk(v[2], v[3]); return r; }
; __device__ __forceinline__ float dpp_shr1(float v) { return __builtin_bit_cast(float, __builtin_amdgcn_update_dpp(0, __builtin_bit_cast(int, v), 0x111, 0xf, 0xf, true)); }
; __device__ __forceinline__ float dpp_shr2(float v) { return __builtin_bit_cast(float, __builtin_amdgcn_update_dpp(0, __builtin_bit_cast(int, v), 0x112, 0xf, 0xf, true)); }
; #define FOR_AI_M _Pragma("unroll") for (int ai = 0; ai < 2; ++ai) _Pragma("unroll") for (int m = 0; m < 4; ++m)
;     __device__ __forceinline__ void operator()(EPI_ARGS) const {
;     ...
;         FOR_AI_M {
;             const int R = ai * 128 + wr * 64 + m * 16 + fr; const int rb = ai * 8 + wr * 4 + m;
;             u32x4 ow;
;             const bool valid = gather ? ((R & 3) >= 2) : (R >= 2);
;             const int orow = gather ? (256 * (R >> 2) + 252 + (R & 3)) : (256 * u.pm + R - 2);
; #pragma unroll
;             for (int n = 0; n < 2; ++n) {
;                 const int cl = wc * 32 + 8 * fq + 4 * n;
;                 f32x4 hA = (f32x4){0.f, 0.f, 0.f, 0.f}, hB = (f32x4){0.f, 0.f, 0.f, 0.f};
;                 if (fr < 2 && rb > 0) { hA = *(const LAS f32x4*)(halo + (((rb - 1) * 2 + fr) * 128 + cl)); if (fr == 0) hB = *(const LAS f32x4*)(halo + (((rb - 1) * 2 + 1) * 128 + cl)); }
;                 const f32x4 g0 = acc[ai][0][m][n], vv = acc[ai][1][m][n];
;                 f32x4 d1, d2;
; #pragma unroll
;                 for (int e = 0; e < 4; ++e) { d1[e] = dpp_shr1(g0[e]); d2[e] = dpp_shr2(g0[e]); }
;                 const f32x4 g1 = d1 + hB, g2 = d2 + hA;
;                 const f32x4 cv = W0[n] * g2 + (W1[n] * g1 + (W2[n] * g0 + BB[n]));
;                 const f32x4 tt = cv * -1.4426950408889634f; f32x4 den;
; #pragma unroll
;                 for (int e = 0; e < 4; ++e) den[e] = __builtin_amdgcn_exp2f(tt[e]);
;                 den = den + 1.0f; f32x4 rc;
; #pragma unroll
;                 for (int e = 0; e < 4; ++e) rc[e] = __builtin_amdgcn_rcpf(den[e]);
;                 const f32x4 o = (cv * rc) * vv;
;                 const u32x2 pk = pack4(o); if (n == 0) { ow.x = pk.x; ow.y = pk.y; } else { ow.z = pk.x; ow.w = pk.y; }
;             }
;             if (valid) *(u32x4*)(ACT + ((size_t)orow * DFF + u.pn * 128 + wc * 32 + 8 * fq)) = ow;
.LBB0_1181:
	s_waitcnt lgkmcnt(0)
	v_mov_b32_dpp v168, v46 row_ror:1 row_mask:0xf bank_mask:0xf
	v_mov_b32_dpp v169, v47 row_ror:1 row_mask:0xf bank_mask:0xf
	s_nop 0
	v_mov_b32_dpp v168, v38 row_shr:1 row_mask:0xf bank_mask:0xf
	v_mov_b32_dpp v169, v39 row_shr:1 row_mask:0xf bank_mask:0xf
	v_pk_fma_f32 v[154:155], v[154:155], v[38:39], v[158:159]
	v_mov_b32_dpp v166, v44 row_ror:1 row_mask:0xf bank_mask:0xf
	v_mov_b32_dpp v167, v45 row_ror:1 row_mask:0xf bank_mask:0xf
	s_nop 0
	v_mov_b32_dpp v166, v36 row_shr:1 row_mask:0xf bank_mask:0xf
	v_mov_b32_dpp v167, v37 row_shr:1 row_mask:0xf bank_mask:0xf
	v_mov_b32_dpp v164, v46 row_ror:2 row_mask:0xf bank_mask:0xf
	v_mov_b32_dpp v165, v47 row_ror:2 row_mask:0xf bank_mask:0xf
	s_nop 0
	v_mov_b32_dpp v164, v38 row_shr:2 row_mask:0xf bank_mask:0xf
	v_mov_b32_dpp v165, v39 row_shr:2 row_mask:0xf bank_mask:0xf
	v_pk_fma_f32 v[152:153], v[152:153], v[36:37], v[156:157]
	v_pk_fma_f32 v[150:151], v[150:151], v[168:169], v[154:155]
	v_mov_b32_dpp v162, v44 row_ror:2 row_mask:0xf bank_mask:0xf
	v_mov_b32_dpp v163, v45 row_ror:2 row_mask:0xf bank_mask:0xf
	s_nop 0
	v_mov_b32_dpp v162, v36 row_shr:2 row_mask:0xf bank_mask:0xf
	v_mov_b32_dpp v163, v37 row_shr:2 row_mask:0xf bank_mask:0xf
	v_pk_fma_f32 v[148:149], v[148:149], v[166:167], v[152:153]
	v_pk_fma_f32 v[146:147], v[146:147], v[164:165], v[150:151]
	v_pk_fma_f32 v[144:145], v[144:145], v[162:163], v[148:149]
	v_mul_f32_e32 v150, 0xbfb8aa3b, v146
	v_mul_f32_e32 v148, 0xbfb8aa3b, v144
	v_mul_f32_e32 v149, 0xbfb8aa3b, v145
	v_exp_f32_e32 v152, v150
	v_mul_f32_e32 v150, 0xbfb8aa3b, v147
	v_exp_f32_e32 v148, v148
	v_exp_f32_e32 v153, v150
	v_exp_f32_e32 v149, v149
	v_mov_b32_e32 v195, v194
	v_mov_b32_e32 v150, v194
	v_pk_add_f32 v[152:153], v[152:153], 1.0 op_sel_hi:[1,0]
	v_pk_add_f32 v[148:149], v[148:149], 1.0 op_sel_hi:[1,0]
	v_rcp_f32_e32 v152, v152
	v_rcp_f32_e32 v148, v148
	v_rcp_f32_e32 v149, v149
	v_rcp_f32_e32 v153, v153
	v_mov_b32_e32 v151, v194
	v_pk_mul_f32 v[6:7], v[6:7], v[150:151]
	v_pk_mul_f32 v[4:5], v[4:5], v[194:195]
	v_pk_mul_f32 v[144:145], v[144:145], v[148:149]
	v_pk_mul_f32 v[146:147], v[146:147], v[152:153]
	v_pk_mul_f32 v[144:145], v[4:5], v[144:145]
	v_pk_mul_f32 v[146:147], v[6:7], v[146:147]
	v_cvt_pk_bf16_f32 v144, v144, v145
	v_mov_b32_e32 v161, 0
	v_cvt_pk_bf16_f32 v145, v146, v147
	v_mov_b32_e32 v162, 0
	v_mov_b32_e32 v163, 0
	v_mov_b32_e32 v146, 0
	v_mov_b32_e32 v147, 0
	v_mov_b32_e32 v148, 0
	v_mov_b32_e32 v149, 0
.LBB0_1185:
	v_pk_mul_f32 v[2:3], v[2:3], v[150:151]
	s_waitcnt lgkmcnt(0)
	v_mov_b32_dpp v146, v40 row_ror:1 row_mask:0xf bank_mask:0xf
	v_mov_b32_dpp v147, v41 row_ror:1 row_mask:0xf bank_mask:0xf
	s_nop 0
	v_mov_b32_dpp v146, v32 row_shr:1 row_mask:0xf bank_mask:0xf
	v_mov_b32_dpp v147, v33 row_shr:1 row_mask:0xf bank_mask:0xf
	v_pk_fma_f32 v[136:137], v[136:137], v[32:33], v[140:141]
	v_mov_b32_dpp v150, v40 row_ror:2 row_mask:0xf bank_mask:0xf
	v_mov_b32_dpp v151, v41 row_ror:2 row_mask:0xf bank_mask:0xf
	s_nop 0
	v_mov_b32_dpp v150, v32 row_shr:2 row_mask:0xf bank_mask:0xf
	v_mov_b32_dpp v151, v33 row_shr:2 row_mask:0xf bank_mask:0xf
	v_pk_fma_f32 v[132:133], v[132:133], v[146:147], v[136:137]
	v_pk_fma_f32 v[128:129], v[128:129], v[150:151], v[132:133]
	v_mul_f32_e32 v132, 0xbfb8aa3b, v128
	v_mul_f32_e32 v133, 0xbfb8aa3b, v129
	v_exp_f32_e32 v132, v132
	v_exp_f32_e32 v133, v133
	v_mov_b32_dpp v148, v42 row_ror:1 row_mask:0xf bank_mask:0xf
	v_mov_b32_dpp v149, v43 row_ror:1 row_mask:0xf bank_mask:0xf
	s_nop 0
	v_mov_b32_dpp v148, v34 row_shr:1 row_mask:0xf bank_mask:0xf
	v_mov_b32_dpp v149, v35 row_shr:1 row_mask:0xf bank_mask:0xf
	v_pk_fma_f32 v[138:139], v[138:139], v[34:35], v[142:143]
	v_mov_b32_dpp v154, v42 row_ror:2 row_mask:0xf bank_mask:0xf
	v_mov_b32_dpp v155, v43 row_ror:2 row_mask:0xf bank_mask:0xf
	s_nop 0
	v_mov_b32_dpp v154, v34 row_shr:2 row_mask:0xf bank_mask:0xf
	v_mov_b32_dpp v155, v35 row_shr:2 row_mask:0xf bank_mask:0xf
	v_pk_fma_f32 v[134:135], v[134:135], v[148:149], v[138:139]
	v_pk_add_f32 v[132:133], v[132:133], 1.0 op_sel_hi:[1,0]
	v_pk_fma_f32 v[130:131], v[130:131], v[154:155], v[134:135]
	v_rcp_f32_e32 v132, v132
	v_mul_f32_e32 v134, 0xbfb8aa3b, v130
	v_mul_f32_e32 v135, 0xbfb8aa3b, v131
	v_exp_f32_e32 v134, v134
	v_exp_f32_e32 v135, v135
	v_rcp_f32_e32 v133, v133
	v_add_u32_e32 v152, 0xb0, v222
	v_pk_mul_f32 v[0:1], v[0:1], v[194:195]
	v_pk_add_f32 v[134:135], v[134:135], 1.0 op_sel_hi:[1,0]
	v_pk_mul_f32 v[128:129], v[128:129], v[132:133]
	v_cmp_lt_i32_e32 vcc, 1, v152
	v_rcp_f32_e32 v134, v134
	v_rcp_f32_e32 v135, v135
	v_pk_mul_f32 v[128:129], v[0:1], v[128:129]
	v_pk_mul_f32 v[130:131], v[130:131], v[134:135]
	v_cvt_pk_bf16_f32 v146, v128, v129
	v_cndmask_b32_e64 v128, 0, 1, vcc
	v_cndmask_b32_e64 v128, v128, v208, s[44:45]
	v_and_b32_e32 v128, 1, v128
	v_cmp_eq_u32_e32 vcc, 1, v128
	v_pk_mul_f32 v[130:131], v[2:3], v[130:131]
	s_nop 0
	v_cvt_pk_bf16_f32 v147, v130, v131
	s_and_saveexec_b64 s[8:9], vcc
	s_cbranch_execz .LBB0_1187
	v_lshlrev_b32_e32 v128, 6, v152
	v_add_u32_e32 v129, s29, v152
	v_or3_b32 v128, v128, v191, s74
	v_cndmask_b32_e64 v130, v129, v128, s[44:45]
	v_mov_b64_e32 v[128:129], s[0:1]
	v_mad_i64_i32 v[128:129], s[12:13], v130, s75, v[128:129]
	v_lshl_add_u64 v[128:129], s[10:11], 1, v[128:129]
	v_lshl_add_u64 v[128:129], s[6:7], 1, v[128:129]
	v_lshl_add_u64 v[128:129], v[192:193], 1, v[128:129]
	global_store_dwordx4 v[128:129], v[144:147], off
